# same store-drain removal in the diff-projection and memory-KV GEMM tile prologues
# baseline (speedup 1.0000x reference)
.LBB0_183:
	v_mov_b32_e32 v128, v154
	s_lshl_b32 s0, s87, 8
	v_ashrrev_i32_e32 v0, 31, v128
	v_lshrrev_b32_e32 v0, 26, v0
	v_add_u32_e32 v0, v128, v0
	v_ashrrev_i32_e32 v1, 6, v0
	v_bfe_i32 v0, v128, 27, 1
	v_lshlrev_b32_e32 v20, 4, v128
	v_lshrrev_b32_e32 v0, 22, v0
	v_add_u32_e32 v0, v20, v0
	v_and_b32_e32 v0, 0xfffffc00, v0
	v_sub_u32_e32 v0, v20, v0
	v_lshrrev_b32_e32 v2, 4, v0
	v_bitop3_b32 v2, v2, v0, 32 bitop3:0x6c
	v_ashrrev_i32_e32 v0, 31, v0
	v_lshrrev_b32_e32 v0, 26, v0
	v_lshlrev_b32_e32 v3, 3, v1
	v_add_u32_e32 v0, v2, v0
	v_and_b32_e32 v3, -16, v3
	v_ashrrev_i32_e32 v4, 6, v0
	v_add_u32_e32 v0, v4, v3
	v_mul_i32_i24_e32 v3, 64, v4
	s_ashr_i32 s1, s0, 31
	v_lshlrev_b32_e32 v1, 5, v1
	v_sub_u32_e32 v2, v2, v3
	s_lshl_b32 s52, s52, 8
	s_lshl_b64 s[56:57], s[0:1], 11
	v_and_b32_e32 v1, 32, v1
	v_ashrrev_i16_sdwa v2, v144, sext(v2) dst_sel:DWORD dst_unused:UNUSED_PAD src0_sel:DWORD src1_sel:BYTE_0
	s_add_u32 s68, s83, s56
	v_add_u32_sdwa v2, v1, sext(v2) dst_sel:DWORD dst_unused:UNUSED_PAD src0_sel:DWORD src1_sel:WORD_0
	v_ashrrev_i32_e32 v1, 31, v0
	s_addc_u32 s69, s84, s57
	v_lshlrev_b64 v[0:1], 11, v[0:1]
	v_ashrrev_i32_e32 v3, 31, v2
	v_lshl_add_u64 v[4:5], s[68:69], 0, v[0:1]
	v_lshlrev_b64 v[2:3], 1, v[2:3]
	v_add_u32_e32 v22, 0x2000, v20
	v_lshl_add_u64 v[8:9], v[4:5], 0, v[2:3]
	v_ashrrev_i32_e32 v4, 31, v22
	v_lshrrev_b32_e32 v4, 22, v4
	v_add_u32_e32 v4, v22, v4
	v_ashrrev_i32_e32 v5, 10, v4
	v_mul_i32_i24_e32 v4, 0x400, v5
	v_sub_u32_e32 v4, v22, v4
	v_lshrrev_b32_e32 v6, 4, v4
	v_bitop3_b32 v6, v6, v4, 32 bitop3:0x6c
	v_ashrrev_i32_e32 v7, 31, v6
	v_lshrrev_b32_e32 v7, 26, v7
	v_add_u32_e32 v7, v6, v7
	v_lshlrev_b32_e32 v4, 3, v5
	v_ashrrev_i32_e32 v10, 6, v7
	v_and_b32_e32 v7, 0xc0, v7
	v_and_b32_e32 v4, -16, v4
	v_lshlrev_b32_e32 v5, 5, v5
	v_sub_u32_e32 v6, v6, v7
	v_add_u32_e32 v4, v10, v4
	v_and_b32_e32 v5, 32, v5
	v_ashrrev_i16_sdwa v6, v144, sext(v6) dst_sel:DWORD dst_unused:UNUSED_PAD src0_sel:DWORD src1_sel:BYTE_0
	v_add_u32_sdwa v6, v5, sext(v6) dst_sel:DWORD dst_unused:UNUSED_PAD src0_sel:DWORD src1_sel:WORD_0
	v_ashrrev_i32_e32 v5, 31, v4
	v_lshlrev_b64 v[4:5], 11, v[4:5]
	s_ashr_i32 s53, s52, 31
	v_lshl_add_u64 v[10:11], s[68:69], 0, v[4:5]
	s_lshl_b64 s[68:69], s[52:53], 11
	v_add_u32_e32 v147, s33, v20
	s_add_u32 s70, s2, s68
	v_readfirstlane_b32 s1, v147
	v_add_u32_e32 v12, s33, v22
	s_addc_u32 s71, s54, s69
	s_mov_b32 m0, s1
	v_readfirstlane_b32 s1, v12
	v_lshl_add_u64 v[12:13], s[70:71], 0, v[0:1]
	v_lshl_add_u64 v[14:15], s[70:71], 0, v[4:5]
	s_or_b32 s70, s0, 0x80
	s_ashr_i32 s71, s70, 31
	s_lshl_b64 s[70:71], s[70:71], 11
	s_add_u32 s70, s83, s70
	v_ashrrev_i32_e32 v7, 31, v6
	s_addc_u32 s71, s84, s71
	v_lshlrev_b64 v[6:7], 1, v[6:7]
	v_add_u32_e32 v153, 0, v20
	v_lshl_add_u64 v[16:17], s[70:71], 0, v[0:1]
	v_lshl_add_u64 v[18:19], s[70:71], 0, v[4:5]
	s_or_b32 s70, s52, 0x80
	s_waitcnt lgkmcnt(0)
	s_waitcnt lgkmcnt(0)
	s_barrier
	global_load_lds_dwordx4 v[8:9], off
	v_lshl_add_u64 v[10:11], v[10:11], 0, v[6:7]
	s_mov_b32 m0, s1
	v_readfirstlane_b32 s1, v153
	v_add_u32_e32 v155, 0x2000, v153
	s_ashr_i32 s71, s70, 31
	global_load_lds_dwordx4 v[10:11], off
	v_lshl_add_u64 v[12:13], v[12:13], 0, v[2:3]
	s_mov_b32 m0, s1
	v_readfirstlane_b32 s1, v155
	v_add_u32_e32 v156, s3, v20
	s_lshl_b64 s[70:71], s[70:71], 11
	global_load_lds_dwordx4 v[12:13], off
	v_lshl_add_u64 v[14:15], v[14:15], 0, v[6:7]
	s_mov_b32 m0, s1
	v_readfirstlane_b32 s1, v156
	v_add_u32_e32 v22, s3, v22
	s_add_u32 s70, s2, s70
	global_load_lds_dwordx4 v[14:15], off
	v_lshl_add_u64 v[16:17], v[16:17], 0, v[2:3]
	s_mov_b32 m0, s1
	v_readfirstlane_b32 s1, v22
	s_addc_u32 s71, s54, s71
	v_add_u32_e32 v158, 0x4000, v153
	global_load_lds_dwordx4 v[16:17], off
	v_lshl_add_u64 v[18:19], v[18:19], 0, v[6:7]
	s_mov_b32 m0, s1
	v_lshl_add_u64 v[22:23], s[70:71], 0, v[0:1]
	v_readfirstlane_b32 s1, v158
	v_add_u32_e32 v159, 0x6000, v153
	global_load_lds_dwordx4 v[18:19], off
	v_lshl_add_u64 v[130:131], v[22:23], 0, v[2:3]
	s_mov_b32 m0, s1
	v_lshl_add_u64 v[22:23], s[70:71], 0, v[4:5]
	v_readfirstlane_b32 s1, v159
	global_load_lds_dwordx4 v[130:131], off
	v_lshl_add_u64 v[132:133], v[22:23], 0, v[6:7]
	s_mov_b32 m0, s1
	v_ashrrev_i32_e32 v21, 8, v128
	global_load_lds_dwordx4 v[132:133], off
	v_cmp_eq_u32_e32 vcc, 1, v21
	s_and_saveexec_b64 s[70:71], vcc
	s_cbranch_execz .LBB0_185
	s_barrier

.LBB0_883:
	v_mov_b32_e32 v144, v154
	s_lshl_b32 s84, s6, 8
	v_ashrrev_i32_e32 v0, 31, v144
	v_lshrrev_b32_e32 v0, 26, v0
	v_add_u32_e32 v0, v144, v0
	v_ashrrev_i32_e32 v1, 6, v0
	v_bfe_i32 v0, v144, 27, 1
	v_lshlrev_b32_e32 v20, 4, v144
	v_lshrrev_b32_e32 v0, 22, v0
	v_add_u32_e32 v0, v20, v0
	v_and_b32_e32 v0, 0xfffffc00, v0
	v_sub_u32_e32 v0, v20, v0
	v_lshrrev_b32_e32 v2, 4, v0
	v_bitop3_b32 v2, v2, v0, 32 bitop3:0x6c
	v_ashrrev_i32_e32 v0, 31, v0
	v_lshrrev_b32_e32 v0, 26, v0
	v_lshlrev_b32_e32 v3, 3, v1
	v_add_u32_e32 v0, v2, v0
	v_and_b32_e32 v3, -16, v3
	v_ashrrev_i32_e32 v4, 6, v0
	v_add_u32_e32 v0, v4, v3
	v_mul_i32_i24_e32 v3, 64, v4
	s_ashr_i32 s85, s84, 31
	v_lshlrev_b32_e32 v1, 5, v1
	v_sub_u32_e32 v2, v2, v3
	s_lshl_b32 s4, s7, 8
	s_lshl_b64 s[6:7], s[84:85], 11
	v_readlane_b32 s12, v255, 45
	v_and_b32_e32 v1, 32, v1
	v_ashrrev_i16_sdwa v2, v159, sext(v2) dst_sel:DWORD dst_unused:UNUSED_PAD src0_sel:DWORD src1_sel:BYTE_0
	s_add_u32 s8, s12, s6
	v_readlane_b32 s13, v255, 46
	v_add_u32_sdwa v2, v1, sext(v2) dst_sel:DWORD dst_unused:UNUSED_PAD src0_sel:DWORD src1_sel:WORD_0
	v_ashrrev_i32_e32 v1, 31, v0
	s_addc_u32 s9, s13, s7
	v_lshlrev_b64 v[0:1], 11, v[0:1]
	v_ashrrev_i32_e32 v3, 31, v2
	v_lshl_add_u64 v[4:5], s[8:9], 0, v[0:1]
	v_lshlrev_b64 v[2:3], 1, v[2:3]
	v_add_u32_e32 v22, 0x2000, v20
	v_lshl_add_u64 v[8:9], v[4:5], 0, v[2:3]
	v_ashrrev_i32_e32 v4, 31, v22
	v_lshrrev_b32_e32 v4, 22, v4
	v_add_u32_e32 v4, v22, v4
	v_ashrrev_i32_e32 v5, 10, v4
	v_mul_i32_i24_e32 v4, 0x400, v5
	v_sub_u32_e32 v4, v22, v4
	v_lshrrev_b32_e32 v6, 4, v4
	v_bitop3_b32 v6, v6, v4, 32 bitop3:0x6c
	v_ashrrev_i32_e32 v7, 31, v6
	v_lshrrev_b32_e32 v7, 26, v7
	v_add_u32_e32 v7, v6, v7
	v_lshlrev_b32_e32 v4, 3, v5
	v_ashrrev_i32_e32 v10, 6, v7
	v_and_b32_e32 v7, 0xc0, v7
	v_add_u32_e32 v147, s33, v20
	v_and_b32_e32 v4, -16, v4
	v_lshlrev_b32_e32 v5, 5, v5
	v_sub_u32_e32 v6, v6, v7
	v_readfirstlane_b32 s5, v147
	v_add_u32_e32 v4, v10, v4
	v_and_b32_e32 v5, 32, v5
	v_ashrrev_i16_sdwa v6, v159, sext(v6) dst_sel:DWORD dst_unused:UNUSED_PAD src0_sel:DWORD src1_sel:BYTE_0
	v_add_u32_e32 v12, s33, v22
	s_mov_b32 m0, s5
	v_add_u32_sdwa v6, v5, sext(v6) dst_sel:DWORD dst_unused:UNUSED_PAD src0_sel:DWORD src1_sel:WORD_0
	v_ashrrev_i32_e32 v5, 31, v4
	v_readfirstlane_b32 s5, v12
	s_waitcnt lgkmcnt(0)
	s_waitcnt lgkmcnt(0)
	s_barrier
	global_load_lds_dwordx4 v[8:9], off
	v_lshlrev_b64 v[4:5], 11, v[4:5]
	s_mov_b32 m0, s5
	s_ashr_i32 s5, s4, 31
	v_lshl_add_u64 v[10:11], s[8:9], 0, v[4:5]
	s_lshl_b64 s[8:9], s[4:5], 11
	v_readlane_b32 s14, v255, 47
	s_add_u32 s10, s14, s8
	v_readlane_b32 s15, v255, 48
	s_addc_u32 s11, s15, s9
	v_lshl_add_u64 v[12:13], s[10:11], 0, v[0:1]
	v_lshl_add_u64 v[14:15], s[10:11], 0, v[4:5]
	s_or_b32 s10, s84, 0x80
	s_ashr_i32 s11, s10, 31
	s_lshl_b64 s[10:11], s[10:11], 11
	s_add_u32 s10, s12, s10
	v_ashrrev_i32_e32 v7, 31, v6
	s_addc_u32 s11, s13, s11
	v_lshlrev_b64 v[6:7], 1, v[6:7]
	v_add_u32_e32 v153, 0, v20
	v_lshl_add_u64 v[16:17], s[10:11], 0, v[0:1]
	v_lshl_add_u64 v[18:19], s[10:11], 0, v[4:5]
	s_or_b32 s10, s4, 0x80
	v_lshl_add_u64 v[10:11], v[10:11], 0, v[6:7]
	v_readfirstlane_b32 s5, v153
	v_add_u32_e32 v160, 0x2000, v153
	s_ashr_i32 s11, s10, 31
	global_load_lds_dwordx4 v[10:11], off
	v_lshl_add_u64 v[12:13], v[12:13], 0, v[2:3]
	s_mov_b32 m0, s5
	v_readfirstlane_b32 s5, v160
	v_add_u32_e32 v162, s3, v20
	s_lshl_b64 s[10:11], s[10:11], 11
	global_load_lds_dwordx4 v[12:13], off
	v_lshl_add_u64 v[14:15], v[14:15], 0, v[6:7]
	s_mov_b32 m0, s5
	v_readfirstlane_b32 s5, v162
	v_add_u32_e32 v22, s3, v22
	s_add_u32 s10, s14, s10
	global_load_lds_dwordx4 v[14:15], off
	v_lshl_add_u64 v[16:17], v[16:17], 0, v[2:3]
	s_mov_b32 m0, s5
	v_readfirstlane_b32 s5, v22
	s_addc_u32 s11, s15, s11
	v_add_u32_e32 v164, 0x4000, v153
	global_load_lds_dwordx4 v[16:17], off
	v_lshl_add_u64 v[18:19], v[18:19], 0, v[6:7]
	s_mov_b32 m0, s5
	v_lshl_add_u64 v[22:23], s[10:11], 0, v[0:1]
	v_readfirstlane_b32 s5, v164
	v_add_u32_e32 v165, 0x6000, v153
	global_load_lds_dwordx4 v[18:19], off
	v_lshl_add_u64 v[132:133], v[22:23], 0, v[2:3]
	s_mov_b32 m0, s5
	v_lshl_add_u64 v[22:23], s[10:11], 0, v[4:5]
	v_readfirstlane_b32 s5, v165
	global_load_lds_dwordx4 v[132:133], off
	v_lshl_add_u64 v[134:135], v[22:23], 0, v[6:7]
	s_mov_b32 m0, s5
	v_ashrrev_i32_e32 v21, 8, v144
	global_load_lds_dwordx4 v[134:135], off
	v_cmp_eq_u32_e32 vcc, 1, v21
	s_and_saveexec_b64 s[10:11], vcc
	s_cbranch_execz .LBB0_885
	s_barrier
